# HG_H3 first MFMA block: fragment reads of k-steps 1-3 issued up front with counted lgkmcnt (was read->wait->MFMA x12)
# speedup vs baseline: 1.0031x; 1.0014x over previous
; #define LAS __attribute__((address_space(3)))
; __device__ __forceinline__ unsigned pk2(float lo, float hi) { f32x2c v = {lo, hi}; return __builtin_bit_cast(unsigned, __builtin_convertvector(v, bf16x2c)); }
; __device__ __forceinline__ void hgrn_h3(LAS unsigned char* lds8, const int e) {
;     ...
;         const int fr = lane & 15, fq = lane >> 4;
;         f32x4 acc[4];
; #pragma unroll
;         for (int I = 0; I < 4; ++I) acc[I] = (f32x4){0.f, 0.f, 0.f, 0.f};
; #pragma unroll
;         for (int ks = 0; ks < 4; ++ks) { const bf16x8 a = *(const LAS bf16x8*)(ST + (16 * wave + fr) * RS128 + 32 * ks + 8 * fq);
; #pragma unroll
;             for (int I = 0; I < 4; ++I) { const bf16x8 bb = *(const LAS bf16x8*)(Qb + (16 * I + fr) * RS128 + 32 * ks + 8 * fq);
;                 acc[I] = __builtin_amdgcn_mfma_f32_16x16x32_bf16(a, bb, acc[I], 0, 0, 0); } }
; #pragma unroll
;         for (int I = 0; I < 4; ++I) {
;             const int rb = 8 * I * (I + 1);
;             f32x4 P[4];
; #pragma unroll
;             for (int Jt = 0; Jt < 4; ++Jt) { P[Jt] = (f32x4){0.f, 0.f, 0.f, 0.f};
;                 if (Jt <= I) {
; #pragma unroll
;                     for (int ks = 0; ks < 4; ++ks) { const bf16x8 a = *(const LAS bf16x8*)(KT + (rb + 16 * Jt + fr) * RS128 + 32 * ks + 8 * fq);
;                         const bf16x8 bb = *(const LAS bf16x8*)(Qt + (16 * I + fr) * RS128 + 32 * ks + 8 * fq);
;                         P[Jt] = __builtin_amdgcn_mfma_f32_16x16x32_bf16(a, bb, P[Jt], 0, 0, 0); }
;                     if (Jt == I) {
; #pragma unroll
;                         for (int r = 0; r < 4; ++r) P[Jt][r] = (4 * fq + r <= fr) ? P[Jt][r] : 0.f; }
;                 } }
; #pragma unroll
;             for (int s = 0; s < 2; ++s) if (2 * s <= I) {
;                 u32x4 pw; pw.x = pk2(P[2 * s][0], P[2 * s][1]); pw.y = pk2(P[2 * s][2], P[2 * s][3]); pw.z = pk2(P[2 * s + 1][0], P[2 * s + 1][1]); pw.w = pk2(P[2 * s + 1][2], P[2 * s + 1][3]);
;                 const s16x4 v0 = *(const LAS s16x4*)(VT + (16 * wave + fr) * RS64 + 32 * s + 4 * fq), v1 = *(const LAS s16x4*)(VT + (16 * wave + fr) * RS64 + 32 * s + 16 + 4 * fq);
;                 const bf16x8 a = (bf16x8){v0[0], v0[1], v0[2], v0[3], v1[0], v1[1], v1[2], v1[3]};
;                 acc[I] = __builtin_amdgcn_mfma_f32_16x16x32_bf16(a, __builtin_bit_cast(bf16x8, pw), acc[I], 0, 0, 0); }
.LBB0_754:
	s_or_b64 exec, exec, s[30:31]
	s_waitcnt lgkmcnt(0)
	s_barrier
	ds_read_b128 v[4:7], v53
	ds_read_b128 v[8:11], v79 offset:17408
	ds_read_b128 v[12:15], v79 offset:21760
	ds_read_b128 v[16:19], v79 offset:26112
	ds_read_b128 v[20:23], v79 offset:30464
	ds_read_b128 v[192:195], v53 offset:64
	ds_read_b128 v[196:199], v79 offset:17472
	ds_read_b128 v[200:203], v79 offset:21824
	ds_read_b128 v[204:207], v79 offset:26176
	ds_read_b128 v[208:211], v79 offset:30528
	ds_read_b128 v[212:215], v53 offset:128
	ds_read_b128 v[216:219], v79 offset:17536
	ds_read_b128 v[220:223], v79 offset:21888
	ds_read_b128 v[224:227], v79 offset:26240
	ds_read_b128 v[228:231], v79 offset:30592
	s_waitcnt lgkmcnt(13)
	v_mfma_f32_16x16x32_bf16 v[8:11], v[4:7], v[8:11], 0
	s_add_i32 s66, s66, s46
	s_add_i32 s4, s4, s5
	s_add_i32 s28, s28, s34
	s_waitcnt lgkmcnt(12)
	v_mfma_f32_16x16x32_bf16 v[12:15], v[4:7], v[12:15], 0
	v_lshl_add_u64 v[32:33], v[32:33], 0, s[2:3]
	s_cmpk_lt_i32 s66, 0x400
	s_waitcnt lgkmcnt(11)
	v_mfma_f32_16x16x32_bf16 v[16:19], v[4:7], v[16:19], 0
	s_waitcnt lgkmcnt(10)
	v_mfma_f32_16x16x32_bf16 v[4:7], v[4:7], v[20:23], 0
	ds_read_b128 v[236:239], v53 offset:192
	ds_read_b128 v[240:243], v79 offset:17600
	ds_read_b128 v[244:247], v79 offset:21952
	s_waitcnt lgkmcnt(11)
	v_mfma_f32_16x16x32_bf16 v[8:11], v[192:195], v[196:199], v[8:11]
	s_waitcnt lgkmcnt(10)
	v_mfma_f32_16x16x32_bf16 v[12:15], v[192:195], v[200:203], v[12:15]
	s_waitcnt lgkmcnt(9)
	v_mfma_f32_16x16x32_bf16 v[16:19], v[192:195], v[204:207], v[16:19]
	s_waitcnt lgkmcnt(8)
	v_mfma_f32_16x16x32_bf16 v[4:7], v[192:195], v[208:211], v[4:7]
	s_waitcnt lgkmcnt(6)
	v_mfma_f32_16x16x32_bf16 v[8:11], v[212:215], v[216:219], v[8:11]
	s_waitcnt lgkmcnt(5)
	v_mfma_f32_16x16x32_bf16 v[12:15], v[212:215], v[220:223], v[12:15]
	s_waitcnt lgkmcnt(4)
	v_mfma_f32_16x16x32_bf16 v[16:19], v[212:215], v[224:227], v[16:19]
	s_waitcnt lgkmcnt(3)
	v_mfma_f32_16x16x32_bf16 v[4:7], v[212:215], v[228:231], v[4:7]
	s_waitcnt lgkmcnt(1)
	v_mfma_f32_16x16x32_bf16 v[8:11], v[236:239], v[240:243], v[8:11]
	s_waitcnt lgkmcnt(0)
	v_mfma_f32_16x16x32_bf16 v[82:85], v[236:239], v[244:247], v[12:15]
	s_nop 2
	ds_read_b128 v[12:15], v79 offset:26304
	s_waitcnt lgkmcnt(0)
	v_mfma_f32_16x16x32_bf16 v[20:23], v[236:239], v[12:15], v[16:19]
	ds_read_b128 v[12:15], v79 offset:30656
	s_waitcnt lgkmcnt(0)
	v_mfma_f32_16x16x32_bf16 v[4:7], v[236:239], v[12:15], v[4:7]
	ds_read_b128 v[12:15], v79 offset:34816
	ds_read_b128 v[16:19], v79
	s_waitcnt lgkmcnt(0)
	v_mfma_f32_16x16x32_bf16 v[12:15], v[12:15], v[16:19], 0
	ds_read_b128 v[16:19], v79 offset:34880
	ds_read_b128 v[24:27], v79 offset:64
	s_waitcnt lgkmcnt(0)
	v_mfma_f32_16x16x32_bf16 v[12:15], v[16:19], v[24:27], v[12:15]
	ds_read_b128 v[16:19], v79 offset:34944
	ds_read_b128 v[24:27], v79 offset:128
	s_waitcnt lgkmcnt(0)
	v_mfma_f32_16x16x32_bf16 v[12:15], v[16:19], v[24:27], v[12:15]
	ds_read_b128 v[16:19], v79 offset:35008
	ds_read_b128 v[24:27], v79 offset:192
	s_waitcnt lgkmcnt(0)
	v_mfma_f32_16x16x32_bf16 v[12:15], v[16:19], v[24:27], v[12:15]
	v_mov_b32_e32 v18, v3
	v_mov_b32_e32 v19, v3
	s_nop 5
	v_cndmask_b32_e64 v12, v12, 0, s[20:21]
	v_cndmask_b32_e64 v13, 0, v13, s[22:23]
	v_cndmask_b32_e64 v14, v14, 0, s[24:25]
	v_cndmask_b32_e64 v15, v15, 0, s[26:27]
	v_cvt_pk_bf16_f32 v16, v12, v13
	v_cvt_pk_bf16_f32 v17, v14, v15
	ds_read2_b64 v[12:15], v81 offset1:4
	s_waitcnt lgkmcnt(0)
	v_mfma_f32_16x16x32_bf16 v[8:11], v[12:15], v[16:19], v[8:11]
	ds_read_b128 v[16:19], v79 offset:39168
	ds_read_b128 v[24:27], v79 offset:4352
	ds_read_b128 v[86:89], v79 offset:39232
	ds_read_b128 v[90:93], v79 offset:4416
	s_waitcnt lgkmcnt(2)
	v_mfma_f32_16x16x32_bf16 v[16:19], v[16:19], v[24:27], 0
	s_waitcnt lgkmcnt(0)
	v_mfma_f32_16x16x32_bf16 v[16:19], v[86:89], v[90:93], v[16:19]
	ds_read_b128 v[86:89], v79 offset:39296
	ds_read_b128 v[94:97], v79 offset:4480
	s_waitcnt lgkmcnt(0)
	v_mfma_f32_16x16x32_bf16 v[16:19], v[86:89], v[94:97], v[16:19]
	ds_read_b128 v[86:89], v79 offset:39360
	ds_read_b128 v[98:101], v79 offset:4544
	s_waitcnt lgkmcnt(0)
	v_mfma_f32_16x16x32_bf16 v[16:19], v[86:89], v[98:101], v[16:19]
	ds_read_b128 v[86:89], v79 offset:43520
	s_waitcnt lgkmcnt(0)
	v_mfma_f32_16x16x32_bf16 v[24:27], v[86:89], v[24:27], 0
	ds_read_b128 v[86:89], v79 offset:43584
	s_nop 3
	v_cvt_pk_bf16_f32 v16, v16, v17
	v_cvt_pk_bf16_f32 v17, v18, v19
	s_waitcnt lgkmcnt(0)
	v_mfma_f32_16x16x32_bf16 v[24:27], v[86:89], v[90:93], v[24:27]
	ds_read_b128 v[86:89], v79 offset:43648
	s_waitcnt lgkmcnt(0)
	v_mfma_f32_16x16x32_bf16 v[24:27], v[86:89], v[94:97], v[24:27]
	ds_read_b128 v[86:89], v79 offset:43712
	s_waitcnt lgkmcnt(0)
	v_mfma_f32_16x16x32_bf16 v[24:27], v[86:89], v[98:101], v[24:27]
	s_nop 7
	v_cndmask_b32_e64 v24, v24, 0, s[20:21]
	v_cndmask_b32_e64 v25, 0, v25, s[22:23]
	v_cndmask_b32_e64 v26, v26, 0, s[24:25]
	v_cndmask_b32_e64 v27, v27, 0, s[26:27]
	v_cvt_pk_bf16_f32 v18, v24, v25
	v_cvt_pk_bf16_f32 v19, v26, v27
	s_nop 1
	v_mfma_f32_16x16x32_bf16 v[16:19], v[12:15], v[16:19], v[82:85]
	ds_read_b128 v[24:27], v79 offset:47872
	s_nop 1
	ds_read_b128 v[82:85], v79 offset:8704
	ds_read_b128 v[86:89], v79 offset:47936
	ds_read_b128 v[90:93], v79 offset:8768
	s_waitcnt lgkmcnt(2)
	v_mfma_f32_16x16x32_bf16 v[24:27], v[24:27], v[82:85], 0
	s_waitcnt lgkmcnt(0)
	v_mfma_f32_16x16x32_bf16 v[24:27], v[86:89], v[90:93], v[24:27]
	ds_read_b128 v[86:89], v79 offset:48000
	ds_read_b128 v[94:97], v79 offset:8832
	s_waitcnt lgkmcnt(0)
; #define LAS __attribute__((address_space(3)))
; __device__ __forceinline__ unsigned pk2(float lo, float hi) { f32x2c v = {lo, hi}; return __builtin_bit_cast(unsigned, __builtin_convertvector(v, bf16x2c)); }
; __device__ __forceinline__ void hgrn_h3(LAS unsigned char* lds8, const int e) {
;     ...
;         for (int I = 0; I < 4; ++I) {
;             const int rb = 8 * I * (I + 1);
;             f32x4 P[4];
; #pragma unroll
;             for (int Jt = 0; Jt < 4; ++Jt) { P[Jt] = (f32x4){0.f, 0.f, 0.f, 0.f};
;                 if (Jt <= I) {
; #pragma unroll
;                     for (int ks = 0; ks < 4; ++ks) { const bf16x8 a = *(const LAS bf16x8*)(KT + (rb + 16 * Jt + fr) * RS128 + 32 * ks + 8 * fq);
;                         const bf16x8 bb = *(const LAS bf16x8*)(Qt + (16 * I + fr) * RS128 + 32 * ks + 8 * fq);
;                         P[Jt] = __builtin_amdgcn_mfma_f32_16x16x32_bf16(a, bb, P[Jt], 0, 0, 0); }
;                     if (Jt == I) {
; #pragma unroll
;                         for (int r = 0; r < 4; ++r) P[Jt][r] = (4 * fq + r <= fr) ? P[Jt][r] : 0.f; }
;                 } }
; #pragma unroll
;             for (int s = 0; s < 2; ++s) if (2 * s <= I) {
;                 u32x4 pw; pw.x = pk2(P[2 * s][0], P[2 * s][1]); pw.y = pk2(P[2 * s][2], P[2 * s][3]); pw.z = pk2(P[2 * s + 1][0], P[2 * s + 1][1]); pw.w = pk2(P[2 * s + 1][2], P[2 * s + 1][3]);
;                 const s16x4 v0 = *(const LAS s16x4*)(VT + (16 * wave + fr) * RS64 + 32 * s + 4 * fq), v1 = *(const LAS s16x4*)(VT + (16 * wave + fr) * RS64 + 32 * s + 16 + 4 * fq);
;                 const bf16x8 a = (bf16x8){v0[0], v0[1], v0[2], v0[3], v1[0], v1[1], v1[2], v1[3]};
;                 acc[I] = __builtin_amdgcn_mfma_f32_16x16x32_bf16(a, __builtin_bit_cast(bf16x8, pw), acc[I], 0, 0, 0); }
;         }
; #pragma unroll
;         for (int I = 0; I < 4; ++I) *(f32x4*)(O0 + (size_t)(m0 + 16 * I + fr) * 1024 + h * 128 + 16 * wave + 4 * fq) = acc[I];
	v_mfma_f32_16x16x32_bf16 v[24:27], v[86:89], v[94:97], v[24:27]
	ds_read_b128 v[86:89], v79 offset:48064
	ds_read_b128 v[98:101], v79 offset:8896
	ds_read_b128 v[102:105], v79 offset:52288
	s_waitcnt lgkmcnt(1)
	v_mfma_f32_16x16x32_bf16 v[24:27], v[86:89], v[98:101], v[24:27]
	ds_read_b128 v[86:89], v79 offset:52224
	s_waitcnt lgkmcnt(0)
	v_mfma_f32_16x16x32_bf16 v[86:89], v[86:89], v[82:85], 0
	s_nop 4
	v_cvt_pk_bf16_f32 v24, v24, v25
	v_cvt_pk_bf16_f32 v25, v26, v27
	v_mfma_f32_16x16x32_bf16 v[86:89], v[102:105], v[90:93], v[86:89]
	ds_read_b128 v[102:105], v79 offset:52352
	s_waitcnt lgkmcnt(0)
	v_mfma_f32_16x16x32_bf16 v[86:89], v[102:105], v[94:97], v[86:89]
	ds_read_b128 v[102:105], v79 offset:52416
	s_waitcnt lgkmcnt(0)
	v_mfma_f32_16x16x32_bf16 v[86:89], v[102:105], v[98:101], v[86:89]
	ds_read_b128 v[102:105], v79 offset:56576
	s_nop 6
	v_cvt_pk_bf16_f32 v26, v86, v87
	s_waitcnt lgkmcnt(0)
	v_mfma_f32_16x16x32_bf16 v[82:85], v[102:105], v[82:85], 0
	ds_read_b128 v[102:105], v79 offset:56640
	v_cvt_pk_bf16_f32 v27, v88, v89
	s_waitcnt lgkmcnt(0)
	v_mfma_f32_16x16x32_bf16 v[82:85], v[102:105], v[90:93], v[82:85]
	ds_read_b128 v[90:93], v79 offset:56704
	s_waitcnt lgkmcnt(0)
	v_mfma_f32_16x16x32_bf16 v[82:85], v[90:93], v[94:97], v[82:85]
	ds_read_b128 v[90:93], v79 offset:56768
	v_mfma_f32_16x16x32_bf16 v[20:23], v[12:15], v[24:27], v[20:23]
	ds_read2_b64 v[24:27], v81 offset0:8 offset1:12
	s_waitcnt lgkmcnt(1)
	v_mfma_f32_16x16x32_bf16 v[82:85], v[90:93], v[98:101], v[82:85]
	s_nop 7
	v_cndmask_b32_e64 v82, v82, 0, s[20:21]
	v_cndmask_b32_e64 v83, 0, v83, s[22:23]
	v_cndmask_b32_e64 v84, v84, 0, s[24:25]
	v_cndmask_b32_e64 v85, v85, 0, s[26:27]
	v_cvt_pk_bf16_f32 v82, v82, v83
	v_cvt_pk_bf16_f32 v83, v84, v85
	v_mov_b32_e32 v84, v3
	v_mov_b32_e32 v85, v3
	s_waitcnt lgkmcnt(0)
	s_nop 0
	v_mfma_f32_16x16x32_bf16 v[20:23], v[24:27], v[82:85], v[20:23]
	ds_read_b128 v[82:85], v79 offset:60928
	ds_read_b128 v[86:89], v79 offset:13056
	ds_read_b128 v[90:93], v79 offset:60992
	ds_read_b128 v[94:97], v79 offset:13120
	s_waitcnt lgkmcnt(2)
	v_mfma_f32_16x16x32_bf16 v[82:85], v[82:85], v[86:89], 0
	s_waitcnt lgkmcnt(0)
	v_mfma_f32_16x16x32_bf16 v[82:85], v[90:93], v[94:97], v[82:85]
	ds_read_b128 v[90:93], v79 offset:61056
	ds_read_b128 v[98:101], v79 offset:13184
	s_waitcnt lgkmcnt(0)
	v_mfma_f32_16x16x32_bf16 v[82:85], v[90:93], v[98:101], v[82:85]
	ds_read_b128 v[90:93], v79 offset:61120
	ds_read_b128 v[102:105], v79 offset:13248
	ds_read_b128 v[106:109], v79 offset:65344
	ds_read_b128 v[110:113], v80 offset:34880
	s_waitcnt lgkmcnt(2)
	v_mfma_f32_16x16x32_bf16 v[82:85], v[90:93], v[102:105], v[82:85]
	ds_read_b128 v[90:93], v79 offset:65280
	s_waitcnt lgkmcnt(0)
	v_mfma_f32_16x16x32_bf16 v[90:93], v[90:93], v[86:89], 0
	s_nop 4
	v_cvt_pk_bf16_f32 v82, v82, v83
	v_cvt_pk_bf16_f32 v83, v84, v85
	v_mfma_f32_16x16x32_bf16 v[90:93], v[106:109], v[94:97], v[90:93]
	ds_read_b128 v[106:109], v79 offset:65408
	s_waitcnt lgkmcnt(0)
	v_mfma_f32_16x16x32_bf16 v[90:93], v[106:109], v[98:101], v[90:93]
	ds_read_b128 v[106:109], v79 offset:65472
	s_waitcnt lgkmcnt(0)
	v_mfma_f32_16x16x32_bf16 v[90:93], v[106:109], v[102:105], v[90:93]
	ds_read_b128 v[106:109], v80 offset:34816
	s_nop 6
	v_cvt_pk_bf16_f32 v84, v90, v91
	s_waitcnt lgkmcnt(0)
	v_mfma_f32_16x16x32_bf16 v[106:109], v[106:109], v[86:89], 0
	v_cvt_pk_bf16_f32 v85, v92, v93
	v_mfma_f32_16x16x32_bf16 v[106:109], v[110:113], v[94:97], v[106:109]
	ds_read_b128 v[110:113], v80 offset:34944
	s_waitcnt lgkmcnt(0)
	v_mfma_f32_16x16x32_bf16 v[106:109], v[110:113], v[98:101], v[106:109]
	ds_read_b128 v[110:113], v80 offset:35008
	s_waitcnt lgkmcnt(0)
	v_mfma_f32_16x16x32_bf16 v[106:109], v[110:113], v[102:105], v[106:109]
	ds_read_b128 v[110:113], v80 offset:39168
	s_waitcnt lgkmcnt(0)
	v_mfma_f32_16x16x32_bf16 v[86:89], v[110:113], v[86:89], 0
	ds_read_b128 v[110:113], v80 offset:39232
	s_waitcnt lgkmcnt(0)
	v_mfma_f32_16x16x32_bf16 v[86:89], v[110:113], v[94:97], v[86:89]
	ds_read_b128 v[94:97], v80 offset:39296
	s_waitcnt lgkmcnt(0)
	v_mfma_f32_16x16x32_bf16 v[86:89], v[94:97], v[98:101], v[86:89]
	ds_read_b128 v[94:97], v80 offset:39360
	s_waitcnt lgkmcnt(0)
	v_mfma_f32_16x16x32_bf16 v[86:89], v[94:97], v[102:105], v[86:89]
	s_nop 7
	v_cndmask_b32_e64 v86, v86, 0, s[20:21]
	v_mfma_f32_16x16x32_bf16 v[4:7], v[12:15], v[82:85], v[4:7]
	v_cndmask_b32_e64 v87, 0, v87, s[22:23]
	v_cndmask_b32_e64 v88, v88, 0, s[24:25]
	v_cndmask_b32_e64 v89, v89, 0, s[26:27]
	v_cvt_pk_bf16_f32 v12, v106, v107
	v_cvt_pk_bf16_f32 v13, v108, v109
	v_cvt_pk_bf16_f32 v14, v86, v87
	v_cvt_pk_bf16_f32 v15, v88, v89
	s_nop 1
	v_mfma_f32_16x16x32_bf16 v[4:7], v[24:27], v[12:15], v[4:7]
	v_or_b32_e32 v12, s35, v52
	v_ashrrev_i32_e32 v13, 31, v12
	v_lshl_add_u64 v[14:15], s[52:53], 2, v[28:29]
	v_lshlrev_b64 v[24:25], 12, v[12:13]
	v_lshl_add_u64 v[24:25], v[14:15], 0, v[24:25]
	global_store_dwordx4 v[24:25], v[8:11], off
	s_nop 1
	v_or_b32_e32 v8, 16, v12
	v_ashrrev_i32_e32 v9, 31, v8
	v_lshlrev_b64 v[8:9], 12, v[8:9]
	v_lshl_add_u64 v[8:9], v[14:15], 0, v[8:9]
	global_store_dwordx4 v[8:9], v[16:19], off
	v_or_b32_e32 v8, 32, v12
	v_ashrrev_i32_e32 v9, 31, v8
	v_lshlrev_b64 v[8:9], 12, v[8:9]
	v_lshl_add_u64 v[8:9], v[14:15], 0, v[8:9]
	global_store_dwordx4 v[8:9], v[20:23], off
	v_or_b32_e32 v8, 48, v12
	v_ashrrev_i32_e32 v9, 31, v8
	v_lshlrev_b64 v[8:9], 12, v[8:9]
	v_lshl_add_u64 v[8:9], v[14:15], 0, v[8:9]
	global_store_dwordx4 v[8:9], v[4:7], off
	s_cbranch_scc0 .LBB0_887
